# speedup vs baseline: 1.0137x; 1.0048x over previous
; __device__ __forceinline__ unsigned cvt_pk_bf16(float lo, float hi) { unsigned r; asm volatile("v_cvt_pk_bf16_f32 %0, %1, %2" : "=v"(r) : "v"(lo), "v"(hi)); return r; }
; __device__ __forceinline__ float sigmoidf_(float x) { return __builtin_amdgcn_rcpf(1.0f + __expf(-x)); }
;     __device__ __forceinline__ void operator()(const f32x4 (&acc)[2][2][4][2], const Unit& u, int wr, int wc, int fr, int fq) const {
;         asm volatile("" : "+v"(fr), "+v"(fq));
;         const int row0 = u.pm * BM + wr * 64 + fr, col0 = u.pn * HALF + wc * 32 + 8 * fq;
;         float rsv[2][4];
; #pragma unroll
;         for (int ai = 0; ai < 2; ++ai)
; #pragma unroll
;             for (int m = 0; m < 4; ++m) rsv[ai][m] = rs_lookup(tab, rt, u.pm, wr * 64 + fr + ai * HALF + m * 16);
; #pragma unroll
;         for (int ai = 0; ai < 2; ++ai)
; #pragma unroll
;             for (int m = 0; m < 4; ++m) { const int row = row0 + ai * HALF + m * 16; bf16_t* rowp = O + (size_t)row * ldc + col0;
;                 const float rs = rsv[ai][m];
;                 float r[8];
; #pragma unroll
;                 for (int n = 0; n < 2; ++n)
; #pragma unroll
;                     for (int j = 0; j < 4; ++j) { const float g = acc[ai][0][m][n][j] * rs, up = acc[ai][1][m][n][j] * rs; r[n * 4 + j] = g * sigmoidf_(g) * up; }
;                 u32x4 w; w.x = cvt_pk_bf16(r[0], r[1]); w.y = cvt_pk_bf16(r[2], r[3]); w.z = cvt_pk_bf16(r[4], r[5]); w.w = cvt_pk_bf16(r[6], r[7]);
;                 __builtin_nontemporal_store(w, (u32x4*)rowp); }
;     }
.LBB0_673:
	s_lshl_b32 s13, s20, 8
	v_mov_b32_e32 v138, v150
	v_mov_b32_e32 v140, v151
	s_add_i32 s13, s13, s62
	s_nop 7
	s_nop 7
	s_cmp_eq_u32 s20, s31
	v_add_u32_e32 v172, s13, v138
	s_movk_i32 s13, 0x300
	s_cselect_b32 s13, 0x200, s13
	s_cmp_lg_u32 s20, s38
	s_cselect_b32 s13, s13, 0x100
	s_cmp_lg_u32 s20, s39
	s_cselect_b32 s13, s13, 0
	s_lshl_b32 s13, s13, 2
	s_add_i32 s13, s13, s66
	v_lshl_add_u32 v138, v138, 2, s13
	ds_read2_b32 v[146:147], v138 offset1:16
	ds_read2_b32 v[144:145], v138 offset0:32 offset1:48
	ds_read2_b32 v[142:143], v138 offset0:128 offset1:144
	ds_read2_b32 v[138:139], v138 offset0:160 offset1:176
	s_waitcnt lgkmcnt(0)
	s_lshl_b32 s13, s21, 7
	s_or_b32 s13, s13, s63
	v_lshl_add_u32 v200, v140, 3, s13
	v_ashrrev_i32_e32 v201, 31, v200
	v_lshlrev_b64 v[200:201], 1, v[200:201]
	v_mov_b64_e32 v[202:203], s[8:9]
	s_movk_i32 s13, 0x2c00
	v_mad_i64_i32 v[204:205], s[20:21], v172, s13, v[202:203]
	s_andn2_b64 vcc, exec, s[0:1]
	s_mov_b64 s[20:21], -1
	s_mov_b32 s82, 0x2c000
	s_mov_b32 s83, 0
	s_mov_b32 s84, 0xdc000
	s_mov_b32 s85, 0
	v_lshl_add_u64 v[204:205], v[204:205], 0, v[200:201]
	v_mul_f32_e32 v124, v124, v146
	v_mul_f32_e32 v120, v120, v146
	v_mul_f32_e32 v125, v125, v146
	v_mul_f32_e32 v121, v121, v146
	v_mul_f32_e32 v126, v126, v146
	v_mul_f32_e32 v122, v122, v146
	v_mul_f32_e32 v127, v127, v146
	v_mul_f32_e32 v123, v123, v146
	v_mul_f32_e32 v116, v116, v146
	v_mul_f32_e32 v112, v112, v146
	v_mul_f32_e32 v117, v117, v146
	v_mul_f32_e32 v113, v113, v146
	v_mul_f32_e32 v118, v118, v146
	v_mul_f32_e32 v114, v114, v146
	v_mul_f32_e32 v119, v119, v146
	v_mul_f32_e32 v115, v115, v146
	v_mul_f32_e32 v206, 0xbfb8aa3b, v124
	v_mul_f32_e32 v207, 0xbfb8aa3b, v125
	v_mul_f32_e32 v208, 0xbfb8aa3b, v126
	v_mul_f32_e32 v209, 0xbfb8aa3b, v127
	v_mul_f32_e32 v210, 0xbfb8aa3b, v116
	v_mul_f32_e32 v211, 0xbfb8aa3b, v117
	v_mul_f32_e32 v212, 0xbfb8aa3b, v118
	v_mul_f32_e32 v213, 0xbfb8aa3b, v119
	v_exp_f32_e32 v206, v206
	v_exp_f32_e32 v207, v207
	v_exp_f32_e32 v208, v208
	v_exp_f32_e32 v209, v209
	v_exp_f32_e32 v210, v210
	v_exp_f32_e32 v211, v211
	v_exp_f32_e32 v212, v212
	v_exp_f32_e32 v213, v213
	v_add_f32_e32 v206, 1.0, v206
	v_add_f32_e32 v207, 1.0, v207
	v_add_f32_e32 v208, 1.0, v208
	v_add_f32_e32 v209, 1.0, v209
	v_add_f32_e32 v210, 1.0, v210
	v_add_f32_e32 v211, 1.0, v211
	v_add_f32_e32 v212, 1.0, v212
	v_add_f32_e32 v213, 1.0, v213
	v_rcp_f32_e32 v206, v206
	v_rcp_f32_e32 v207, v207
	v_rcp_f32_e32 v208, v208
	v_rcp_f32_e32 v209, v209
	v_rcp_f32_e32 v210, v210
	v_rcp_f32_e32 v211, v211
	v_rcp_f32_e32 v212, v212
	v_rcp_f32_e32 v213, v213
	v_mul_f32_e32 v124, v124, v206
	v_mul_f32_e32 v125, v125, v207
	v_mul_f32_e32 v126, v126, v208
	v_mul_f32_e32 v127, v127, v209
	v_mul_f32_e32 v116, v116, v210
	v_mul_f32_e32 v117, v117, v211
	v_mul_f32_e32 v118, v118, v212
	v_mul_f32_e32 v119, v119, v213
	v_mul_f32_e32 v120, v120, v124
	v_mul_f32_e32 v121, v121, v125
	v_mul_f32_e32 v122, v122, v126
	v_mul_f32_e32 v123, v123, v127
	v_mul_f32_e32 v112, v112, v116
	v_mul_f32_e32 v113, v113, v117
	v_mul_f32_e32 v114, v114, v118
	v_mul_f32_e32 v115, v115, v119
	v_cvt_pk_bf16_f32 v214, v120, v121
	v_cvt_pk_bf16_f32 v215, v122, v123
	v_cvt_pk_bf16_f32 v216, v112, v113
	v_cvt_pk_bf16_f32 v217, v114, v115
	global_store_dwordx4 v[204:205], v[214:217], off nt
	v_lshl_add_u64 v[222:223], v[204:205], 0, s[82:83]
	v_mul_f32_e32 v108, v108, v147
	v_mul_f32_e32 v104, v104, v147
	v_mul_f32_e32 v109, v109, v147
	v_mul_f32_e32 v105, v105, v147
	v_mul_f32_e32 v110, v110, v147
	v_mul_f32_e32 v106, v106, v147
	v_mul_f32_e32 v111, v111, v147
	v_mul_f32_e32 v107, v107, v147
	v_mul_f32_e32 v100, v100, v147
	v_mul_f32_e32 v96, v96, v147
	v_mul_f32_e32 v101, v101, v147
	v_mul_f32_e32 v97, v97, v147
	v_mul_f32_e32 v102, v102, v147
	v_mul_f32_e32 v98, v98, v147
	v_mul_f32_e32 v103, v103, v147
	v_mul_f32_e32 v99, v99, v147
	v_mul_f32_e32 v206, 0xbfb8aa3b, v108
	v_mul_f32_e32 v207, 0xbfb8aa3b, v109
	v_mul_f32_e32 v208, 0xbfb8aa3b, v110
	v_mul_f32_e32 v209, 0xbfb8aa3b, v111
	v_mul_f32_e32 v210, 0xbfb8aa3b, v100
	v_mul_f32_e32 v211, 0xbfb8aa3b, v101
	v_mul_f32_e32 v212, 0xbfb8aa3b, v102
	v_mul_f32_e32 v213, 0xbfb8aa3b, v103
	v_exp_f32_e32 v206, v206
	v_exp_f32_e32 v207, v207
	v_exp_f32_e32 v208, v208
	v_exp_f32_e32 v209, v209
	v_exp_f32_e32 v210, v210
	v_exp_f32_e32 v211, v211
	v_exp_f32_e32 v212, v212
	v_exp_f32_e32 v213, v213
	v_add_f32_e32 v206, 1.0, v206
	v_add_f32_e32 v207, 1.0, v207
	v_add_f32_e32 v208, 1.0, v208
	v_add_f32_e32 v209, 1.0, v209
	v_add_f32_e32 v210, 1.0, v210
	v_add_f32_e32 v211, 1.0, v211
	v_add_f32_e32 v212, 1.0, v212
	v_add_f32_e32 v213, 1.0, v213
	v_rcp_f32_e32 v206, v206
	v_rcp_f32_e32 v207, v207
	v_rcp_f32_e32 v208, v208
	v_rcp_f32_e32 v209, v209
	v_rcp_f32_e32 v210, v210
	v_rcp_f32_e32 v211, v211
	v_rcp_f32_e32 v212, v212
	v_rcp_f32_e32 v213, v213
	v_mul_f32_e32 v108, v108, v206
	v_mul_f32_e32 v109, v109, v207
	v_mul_f32_e32 v110, v110, v208
	v_mul_f32_e32 v111, v111, v209
	v_mul_f32_e32 v100, v100, v210
	v_mul_f32_e32 v101, v101, v211
	v_mul_f32_e32 v102, v102, v212
	v_mul_f32_e32 v103, v103, v213
	v_mul_f32_e32 v104, v104, v108
	v_mul_f32_e32 v105, v105, v109
	v_mul_f32_e32 v106, v106, v110
	v_mul_f32_e32 v107, v107, v111
	v_mul_f32_e32 v96, v96, v100
	v_mul_f32_e32 v97, v97, v101
	v_mul_f32_e32 v98, v98, v102
	v_mul_f32_e32 v99, v99, v103
	v_cvt_pk_bf16_f32 v218, v104, v105
	v_cvt_pk_bf16_f32 v219, v106, v107
	v_cvt_pk_bf16_f32 v220, v96, v97
	v_cvt_pk_bf16_f32 v221, v98, v99
	global_store_dwordx4 v[222:223], v[218:221], off nt
	v_lshl_add_u64 v[204:205], v[222:223], 0, s[82:83]
	v_mul_f32_e32 v92, v92, v144
	v_mul_f32_e32 v88, v88, v144
; __device__ __forceinline__ unsigned cvt_pk_bf16(float lo, float hi) { unsigned r; asm volatile("v_cvt_pk_bf16_f32 %0, %1, %2" : "=v"(r) : "v"(lo), "v"(hi)); return r; }
; __device__ __forceinline__ float sigmoidf_(float x) { return __builtin_amdgcn_rcpf(1.0f + __expf(-x)); }
;     __device__ __forceinline__ void operator()(const f32x4 (&acc)[2][2][4][2], const Unit& u, int wr, int wc, int fr, int fq) const {
;     ...
;             for (int m = 0; m < 4; ++m) { const int row = row0 + ai * HALF + m * 16; bf16_t* rowp = O + (size_t)row * ldc + col0;
;                 const float rs = rsv[ai][m];
;                 float r[8];
; #pragma unroll
;                 for (int n = 0; n < 2; ++n)
; #pragma unroll
;                     for (int j = 0; j < 4; ++j) { const float g = acc[ai][0][m][n][j] * rs, up = acc[ai][1][m][n][j] * rs; r[n * 4 + j] = g * sigmoidf_(g) * up; }
;                 u32x4 w; w.x = cvt_pk_bf16(r[0], r[1]); w.y = cvt_pk_bf16(r[2], r[3]); w.z = cvt_pk_bf16(r[4], r[5]); w.w = cvt_pk_bf16(r[6], r[7]);
;                 __builtin_nontemporal_store(w, (u32x4*)rowp); }
	v_mul_f32_e32 v93, v93, v144
	v_mul_f32_e32 v89, v89, v144
	v_mul_f32_e32 v94, v94, v144
	v_mul_f32_e32 v90, v90, v144
	v_mul_f32_e32 v95, v95, v144
	v_mul_f32_e32 v91, v91, v144
	v_mul_f32_e32 v84, v84, v144
	v_mul_f32_e32 v80, v80, v144
	v_mul_f32_e32 v85, v85, v144
	v_mul_f32_e32 v81, v81, v144
	v_mul_f32_e32 v86, v86, v144
	v_mul_f32_e32 v82, v82, v144
	v_mul_f32_e32 v87, v87, v144
	v_mul_f32_e32 v83, v83, v144
	v_mul_f32_e32 v206, 0xbfb8aa3b, v92
	v_mul_f32_e32 v207, 0xbfb8aa3b, v93
	v_mul_f32_e32 v208, 0xbfb8aa3b, v94
	v_mul_f32_e32 v209, 0xbfb8aa3b, v95
	v_mul_f32_e32 v210, 0xbfb8aa3b, v84
	v_mul_f32_e32 v211, 0xbfb8aa3b, v85
	v_mul_f32_e32 v212, 0xbfb8aa3b, v86
	v_mul_f32_e32 v213, 0xbfb8aa3b, v87
	v_exp_f32_e32 v206, v206
	v_exp_f32_e32 v207, v207
	v_exp_f32_e32 v208, v208
	v_exp_f32_e32 v209, v209
	v_exp_f32_e32 v210, v210
	v_exp_f32_e32 v211, v211
	v_exp_f32_e32 v212, v212
	v_exp_f32_e32 v213, v213
	v_add_f32_e32 v206, 1.0, v206
	v_add_f32_e32 v207, 1.0, v207
	v_add_f32_e32 v208, 1.0, v208
	v_add_f32_e32 v209, 1.0, v209
	v_add_f32_e32 v210, 1.0, v210
	v_add_f32_e32 v211, 1.0, v211
	v_add_f32_e32 v212, 1.0, v212
	v_add_f32_e32 v213, 1.0, v213
	v_rcp_f32_e32 v206, v206
	v_rcp_f32_e32 v207, v207
	v_rcp_f32_e32 v208, v208
	v_rcp_f32_e32 v209, v209
	v_rcp_f32_e32 v210, v210
	v_rcp_f32_e32 v211, v211
	v_rcp_f32_e32 v212, v212
	v_rcp_f32_e32 v213, v213
	v_mul_f32_e32 v92, v92, v206
	v_mul_f32_e32 v93, v93, v207
	v_mul_f32_e32 v94, v94, v208
	v_mul_f32_e32 v95, v95, v209
	v_mul_f32_e32 v84, v84, v210
	v_mul_f32_e32 v85, v85, v211
	v_mul_f32_e32 v86, v86, v212
	v_mul_f32_e32 v87, v87, v213
	v_mul_f32_e32 v88, v88, v92
	v_mul_f32_e32 v89, v89, v93
	v_mul_f32_e32 v90, v90, v94
	v_mul_f32_e32 v91, v91, v95
	v_mul_f32_e32 v80, v80, v84
	v_mul_f32_e32 v81, v81, v85
	v_mul_f32_e32 v82, v82, v86
	v_mul_f32_e32 v83, v83, v87
	v_cvt_pk_bf16_f32 v214, v88, v89
	v_cvt_pk_bf16_f32 v215, v90, v91
	v_cvt_pk_bf16_f32 v216, v80, v81
	v_cvt_pk_bf16_f32 v217, v82, v83
	global_store_dwordx4 v[204:205], v[214:217], off nt
	v_lshl_add_u64 v[222:223], v[204:205], 0, s[82:83]
	v_mul_f32_e32 v76, v76, v145
	v_mul_f32_e32 v72, v72, v145
	v_mul_f32_e32 v77, v77, v145
	v_mul_f32_e32 v73, v73, v145
	v_mul_f32_e32 v78, v78, v145
	v_mul_f32_e32 v74, v74, v145
	v_mul_f32_e32 v79, v79, v145
	v_mul_f32_e32 v75, v75, v145
	v_mul_f32_e32 v68, v68, v145
	v_mul_f32_e32 v64, v64, v145
	v_mul_f32_e32 v69, v69, v145
	v_mul_f32_e32 v65, v65, v145
	v_mul_f32_e32 v70, v70, v145
	v_mul_f32_e32 v66, v66, v145
	v_mul_f32_e32 v71, v71, v145
	v_mul_f32_e32 v67, v67, v145
	v_mul_f32_e32 v206, 0xbfb8aa3b, v76
	v_mul_f32_e32 v207, 0xbfb8aa3b, v77
	v_mul_f32_e32 v208, 0xbfb8aa3b, v78
	v_mul_f32_e32 v209, 0xbfb8aa3b, v79
	v_mul_f32_e32 v210, 0xbfb8aa3b, v68
	v_mul_f32_e32 v211, 0xbfb8aa3b, v69
	v_mul_f32_e32 v212, 0xbfb8aa3b, v70
	v_mul_f32_e32 v213, 0xbfb8aa3b, v71
	v_exp_f32_e32 v206, v206
	v_exp_f32_e32 v207, v207
	v_exp_f32_e32 v208, v208
	v_exp_f32_e32 v209, v209
	v_exp_f32_e32 v210, v210
	v_exp_f32_e32 v211, v211
	v_exp_f32_e32 v212, v212
	v_exp_f32_e32 v213, v213
	v_add_f32_e32 v206, 1.0, v206
	v_add_f32_e32 v207, 1.0, v207
	v_add_f32_e32 v208, 1.0, v208
	v_add_f32_e32 v209, 1.0, v209
	v_add_f32_e32 v210, 1.0, v210
	v_add_f32_e32 v211, 1.0, v211
	v_add_f32_e32 v212, 1.0, v212
	v_add_f32_e32 v213, 1.0, v213
	v_rcp_f32_e32 v206, v206
	v_rcp_f32_e32 v207, v207
	v_rcp_f32_e32 v208, v208
	v_rcp_f32_e32 v209, v209
	v_rcp_f32_e32 v210, v210
	v_rcp_f32_e32 v211, v211
	v_rcp_f32_e32 v212, v212
	v_rcp_f32_e32 v213, v213
	v_mul_f32_e32 v76, v76, v206
	v_mul_f32_e32 v77, v77, v207
	v_mul_f32_e32 v78, v78, v208
	v_mul_f32_e32 v79, v79, v209
	v_mul_f32_e32 v68, v68, v210
	v_mul_f32_e32 v69, v69, v211
	v_mul_f32_e32 v70, v70, v212
	v_mul_f32_e32 v71, v71, v213
	v_mul_f32_e32 v72, v72, v76
	v_mul_f32_e32 v73, v73, v77
	v_mul_f32_e32 v74, v74, v78
	v_mul_f32_e32 v75, v75, v79
	v_mul_f32_e32 v64, v64, v68
	v_mul_f32_e32 v65, v65, v69
	v_mul_f32_e32 v66, v66, v70
	v_mul_f32_e32 v67, v67, v71
	v_cvt_pk_bf16_f32 v218, v72, v73
	v_cvt_pk_bf16_f32 v219, v74, v75
	v_cvt_pk_bf16_f32 v220, v64, v65
	v_cvt_pk_bf16_f32 v221, v66, v67
	global_store_dwordx4 v[222:223], v[218:221], off nt
	v_lshl_add_u64 v[204:205], v[222:223], 0, s[84:85]
	v_mul_f32_e32 v60, v60, v142
	v_mul_f32_e32 v56, v56, v142
	v_mul_f32_e32 v61, v61, v142
	v_mul_f32_e32 v57, v57, v142
	v_mul_f32_e32 v62, v62, v142
	v_mul_f32_e32 v58, v58, v142
	v_mul_f32_e32 v63, v63, v142
	v_mul_f32_e32 v59, v59, v142
	v_mul_f32_e32 v52, v52, v142
	v_mul_f32_e32 v48, v48, v142
	v_mul_f32_e32 v53, v53, v142
	v_mul_f32_e32 v49, v49, v142
	v_mul_f32_e32 v54, v54, v142
	v_mul_f32_e32 v50, v50, v142
	v_mul_f32_e32 v55, v55, v142
	v_mul_f32_e32 v51, v51, v142
	v_mul_f32_e32 v206, 0xbfb8aa3b, v60
	v_mul_f32_e32 v207, 0xbfb8aa3b, v61
	v_mul_f32_e32 v208, 0xbfb8aa3b, v62
	v_mul_f32_e32 v209, 0xbfb8aa3b, v63
	v_mul_f32_e32 v210, 0xbfb8aa3b, v52
	v_mul_f32_e32 v211, 0xbfb8aa3b, v53
	v_mul_f32_e32 v212, 0xbfb8aa3b, v54
	v_mul_f32_e32 v213, 0xbfb8aa3b, v55
	v_exp_f32_e32 v206, v206
	v_exp_f32_e32 v207, v207
	v_exp_f32_e32 v208, v208
	v_exp_f32_e32 v209, v209
	v_exp_f32_e32 v210, v210
	v_exp_f32_e32 v211, v211
	v_exp_f32_e32 v212, v212
	v_exp_f32_e32 v213, v213
	v_add_f32_e32 v206, 1.0, v206
	v_add_f32_e32 v207, 1.0, v207
	v_add_f32_e32 v208, 1.0, v208
	v_add_f32_e32 v209, 1.0, v209
	v_add_f32_e32 v210, 1.0, v210
	v_add_f32_e32 v211, 1.0, v211
	v_add_f32_e32 v212, 1.0, v212
	v_add_f32_e32 v213, 1.0, v213
	v_rcp_f32_e32 v206, v206
	v_rcp_f32_e32 v207, v207
	v_rcp_f32_e32 v208, v208
	v_rcp_f32_e32 v209, v209
	v_rcp_f32_e32 v210, v210
	v_rcp_f32_e32 v211, v211
; __device__ __forceinline__ unsigned cvt_pk_bf16(float lo, float hi) { unsigned r; asm volatile("v_cvt_pk_bf16_f32 %0, %1, %2" : "=v"(r) : "v"(lo), "v"(hi)); return r; }
; __device__ __forceinline__ float sigmoidf_(float x) { return __builtin_amdgcn_rcpf(1.0f + __expf(-x)); }
;     __device__ __forceinline__ void operator()(const f32x4 (&acc)[2][2][4][2], const Unit& u, int wr, int wc, int fr, int fq) const {
;     ...
;             for (int m = 0; m < 4; ++m) { const int row = row0 + ai * HALF + m * 16; bf16_t* rowp = O + (size_t)row * ldc + col0;
;                 const float rs = rsv[ai][m];
;                 float r[8];
; #pragma unroll
;                 for (int n = 0; n < 2; ++n)
; #pragma unroll
;                     for (int j = 0; j < 4; ++j) { const float g = acc[ai][0][m][n][j] * rs, up = acc[ai][1][m][n][j] * rs; r[n * 4 + j] = g * sigmoidf_(g) * up; }
;                 u32x4 w; w.x = cvt_pk_bf16(r[0], r[1]); w.y = cvt_pk_bf16(r[2], r[3]); w.z = cvt_pk_bf16(r[4], r[5]); w.w = cvt_pk_bf16(r[6], r[7]);
;                 __builtin_nontemporal_store(w, (u32x4*)rowp); }
	v_rcp_f32_e32 v212, v212
	v_rcp_f32_e32 v213, v213
	v_mul_f32_e32 v60, v60, v206
	v_mul_f32_e32 v61, v61, v207
	v_mul_f32_e32 v62, v62, v208
	v_mul_f32_e32 v63, v63, v209
	v_mul_f32_e32 v52, v52, v210
	v_mul_f32_e32 v53, v53, v211
	v_mul_f32_e32 v54, v54, v212
	v_mul_f32_e32 v55, v55, v213
	v_mul_f32_e32 v56, v56, v60
	v_mul_f32_e32 v57, v57, v61
	v_mul_f32_e32 v58, v58, v62
	v_mul_f32_e32 v59, v59, v63
	v_mul_f32_e32 v48, v48, v52
	v_mul_f32_e32 v49, v49, v53
	v_mul_f32_e32 v50, v50, v54
	v_mul_f32_e32 v51, v51, v55
	v_cvt_pk_bf16_f32 v214, v56, v57
	v_cvt_pk_bf16_f32 v215, v58, v59
	v_cvt_pk_bf16_f32 v216, v48, v49
	v_cvt_pk_bf16_f32 v217, v50, v51
	global_store_dwordx4 v[204:205], v[214:217], off nt
	v_lshl_add_u64 v[222:223], v[204:205], 0, s[82:83]
	v_mul_f32_e32 v44, v44, v143
	v_mul_f32_e32 v40, v40, v143
	v_mul_f32_e32 v45, v45, v143
	v_mul_f32_e32 v41, v41, v143
	v_mul_f32_e32 v46, v46, v143
	v_mul_f32_e32 v42, v42, v143
	v_mul_f32_e32 v47, v47, v143
	v_mul_f32_e32 v43, v43, v143
	v_mul_f32_e32 v36, v36, v143
	v_mul_f32_e32 v32, v32, v143
	v_mul_f32_e32 v37, v37, v143
	v_mul_f32_e32 v33, v33, v143
	v_mul_f32_e32 v38, v38, v143
	v_mul_f32_e32 v34, v34, v143
	v_mul_f32_e32 v39, v39, v143
	v_mul_f32_e32 v35, v35, v143
	v_mul_f32_e32 v206, 0xbfb8aa3b, v44
	v_mul_f32_e32 v207, 0xbfb8aa3b, v45
	v_mul_f32_e32 v208, 0xbfb8aa3b, v46
	v_mul_f32_e32 v209, 0xbfb8aa3b, v47
	v_mul_f32_e32 v210, 0xbfb8aa3b, v36
	v_mul_f32_e32 v211, 0xbfb8aa3b, v37
	v_mul_f32_e32 v212, 0xbfb8aa3b, v38
	v_mul_f32_e32 v213, 0xbfb8aa3b, v39
	v_exp_f32_e32 v206, v206
	v_exp_f32_e32 v207, v207
	v_exp_f32_e32 v208, v208
	v_exp_f32_e32 v209, v209
	v_exp_f32_e32 v210, v210
	v_exp_f32_e32 v211, v211
	v_exp_f32_e32 v212, v212
	v_exp_f32_e32 v213, v213
	v_add_f32_e32 v206, 1.0, v206
	v_add_f32_e32 v207, 1.0, v207
	v_add_f32_e32 v208, 1.0, v208
	v_add_f32_e32 v209, 1.0, v209
	v_add_f32_e32 v210, 1.0, v210
	v_add_f32_e32 v211, 1.0, v211
	v_add_f32_e32 v212, 1.0, v212
	v_add_f32_e32 v213, 1.0, v213
	v_rcp_f32_e32 v206, v206
	v_rcp_f32_e32 v207, v207
	v_rcp_f32_e32 v208, v208
	v_rcp_f32_e32 v209, v209
	v_rcp_f32_e32 v210, v210
	v_rcp_f32_e32 v211, v211
	v_rcp_f32_e32 v212, v212
	v_rcp_f32_e32 v213, v213
	v_mul_f32_e32 v44, v44, v206
	v_mul_f32_e32 v45, v45, v207
	v_mul_f32_e32 v46, v46, v208
	v_mul_f32_e32 v47, v47, v209
	v_mul_f32_e32 v36, v36, v210
	v_mul_f32_e32 v37, v37, v211
	v_mul_f32_e32 v38, v38, v212
	v_mul_f32_e32 v39, v39, v213
	v_mul_f32_e32 v40, v40, v44
	v_mul_f32_e32 v41, v41, v45
	v_mul_f32_e32 v42, v42, v46
	v_mul_f32_e32 v43, v43, v47
	v_mul_f32_e32 v32, v32, v36
	v_mul_f32_e32 v33, v33, v37
	v_mul_f32_e32 v34, v34, v38
	v_mul_f32_e32 v35, v35, v39
	v_cvt_pk_bf16_f32 v218, v40, v41
	v_cvt_pk_bf16_f32 v219, v42, v43
	v_cvt_pk_bf16_f32 v220, v32, v33
	v_cvt_pk_bf16_f32 v221, v34, v35
	global_store_dwordx4 v[222:223], v[218:221], off nt
	v_lshl_add_u64 v[204:205], v[222:223], 0, s[82:83]
	v_mul_f32_e32 v28, v28, v138
	v_mul_f32_e32 v24, v24, v138
	v_mul_f32_e32 v29, v29, v138
	v_mul_f32_e32 v25, v25, v138
	v_mul_f32_e32 v30, v30, v138
	v_mul_f32_e32 v26, v26, v138
	v_mul_f32_e32 v31, v31, v138
	v_mul_f32_e32 v27, v27, v138
	v_mul_f32_e32 v20, v20, v138
	v_mul_f32_e32 v16, v16, v138
	v_mul_f32_e32 v21, v21, v138
	v_mul_f32_e32 v17, v17, v138
	v_mul_f32_e32 v22, v22, v138
	v_mul_f32_e32 v18, v18, v138
	v_mul_f32_e32 v23, v23, v138
	v_mul_f32_e32 v19, v19, v138
	v_mul_f32_e32 v206, 0xbfb8aa3b, v28
	v_mul_f32_e32 v207, 0xbfb8aa3b, v29
	v_mul_f32_e32 v208, 0xbfb8aa3b, v30
	v_mul_f32_e32 v209, 0xbfb8aa3b, v31
	v_mul_f32_e32 v210, 0xbfb8aa3b, v20
	v_mul_f32_e32 v211, 0xbfb8aa3b, v21
; __device__ __forceinline__ unsigned cvt_pk_bf16(float lo, float hi) { unsigned r; asm volatile("v_cvt_pk_bf16_f32 %0, %1, %2" : "=v"(r) : "v"(lo), "v"(hi)); return r; }
; __device__ __forceinline__ float sigmoidf_(float x) { return __builtin_amdgcn_rcpf(1.0f + __expf(-x)); }
; #define PG8_BAR __builtin_amdgcn_s_barrier()
; #define a (*get_args())
;     __device__ __forceinline__ void operator()(const f32x4 (&acc)[2][2][4][2], const Unit& u, int wr, int wc, int fr, int fq) const {
;     ...
;             for (int m = 0; m < 4; ++m) { const int row = row0 + ai * HALF + m * 16; bf16_t* rowp = O + (size_t)row * ldc + col0;
;                 const float rs = rsv[ai][m];
;                 float r[8];
; #pragma unroll
;                 for (int n = 0; n < 2; ++n)
; #pragma unroll
;                     for (int j = 0; j < 4; ++j) { const float g = acc[ai][0][m][n][j] * rs, up = acc[ai][1][m][n][j] * rs; r[n * 4 + j] = g * sigmoidf_(g) * up; }
;                 u32x4 w; w.x = cvt_pk_bf16(r[0], r[1]); w.y = cvt_pk_bf16(r[2], r[3]); w.z = cvt_pk_bf16(r[4], r[5]); w.w = cvt_pk_bf16(r[6], r[7]);
;                 __builtin_nontemporal_store(w, (u32x4*)rowp); }
; template <class Epi, class Sched>
; __device__ __forceinline__ void gemm_phase(const int tid, LAS unsigned char* lds, const Gemm g, const Sched& S, const Epi& E) {
;     ...
;         if (!has_next) break;
; #pragma unroll
;         for (int a = 0; a < 2; ++a)
; #pragma unroll
;             for (int b = 0; b < 2; ++b)
; #pragma unroll
;                 for (int m = 0; m < 4; ++m)
; #pragma unroll
;                     for (int n = 0; n < 2; ++n) acc[a][b][m][n] = (f32x4){0.f, 0.f, 0.f, 0.f};
;         cur = nxt; cA = nA; cB = nB; ++ui;
;         if (wr == 1) PG8_BAR;
	v_mul_f32_e32 v212, 0xbfb8aa3b, v22
	v_mul_f32_e32 v213, 0xbfb8aa3b, v23
	v_exp_f32_e32 v206, v206
	v_exp_f32_e32 v207, v207
	v_exp_f32_e32 v208, v208
	v_exp_f32_e32 v209, v209
	v_exp_f32_e32 v210, v210
	v_exp_f32_e32 v211, v211
	v_exp_f32_e32 v212, v212
	v_exp_f32_e32 v213, v213
	v_add_f32_e32 v206, 1.0, v206
	v_add_f32_e32 v207, 1.0, v207
	v_add_f32_e32 v208, 1.0, v208
	v_add_f32_e32 v209, 1.0, v209
	v_add_f32_e32 v210, 1.0, v210
	v_add_f32_e32 v211, 1.0, v211
	v_add_f32_e32 v212, 1.0, v212
	v_add_f32_e32 v213, 1.0, v213
	v_rcp_f32_e32 v206, v206
	v_rcp_f32_e32 v207, v207
	v_rcp_f32_e32 v208, v208
	v_rcp_f32_e32 v209, v209
	v_rcp_f32_e32 v210, v210
	v_rcp_f32_e32 v211, v211
	v_rcp_f32_e32 v212, v212
	v_rcp_f32_e32 v213, v213
	v_mul_f32_e32 v28, v28, v206
	v_mul_f32_e32 v29, v29, v207
	v_mul_f32_e32 v30, v30, v208
	v_mul_f32_e32 v31, v31, v209
	v_mul_f32_e32 v20, v20, v210
	v_mul_f32_e32 v21, v21, v211
	v_mul_f32_e32 v22, v22, v212
	v_mul_f32_e32 v23, v23, v213
	v_mul_f32_e32 v24, v24, v28
	v_mul_f32_e32 v25, v25, v29
	v_mul_f32_e32 v26, v26, v30
	v_mul_f32_e32 v27, v27, v31
	v_mul_f32_e32 v16, v16, v20
	v_mul_f32_e32 v17, v17, v21
	v_mul_f32_e32 v18, v18, v22
	v_mul_f32_e32 v19, v19, v23
	v_cvt_pk_bf16_f32 v214, v24, v25
	v_cvt_pk_bf16_f32 v215, v26, v27
	v_cvt_pk_bf16_f32 v216, v16, v17
	v_cvt_pk_bf16_f32 v217, v18, v19
	global_store_dwordx4 v[204:205], v[214:217], off nt
	v_lshl_add_u64 v[222:223], v[204:205], 0, s[82:83]
	v_mul_f32_e32 v12, v12, v139
	v_mul_f32_e32 v8, v8, v139
	v_mul_f32_e32 v13, v13, v139
	v_mul_f32_e32 v9, v9, v139
	v_mul_f32_e32 v14, v14, v139
	v_mul_f32_e32 v10, v10, v139
	v_mul_f32_e32 v15, v15, v139
	v_mul_f32_e32 v11, v11, v139
	v_mul_f32_e32 v4, v4, v139
	v_mul_f32_e32 v0, v0, v139
	v_mul_f32_e32 v5, v5, v139
	v_mul_f32_e32 v1, v1, v139
	v_mul_f32_e32 v6, v6, v139
	v_mul_f32_e32 v2, v2, v139
	v_mul_f32_e32 v7, v7, v139
	v_mul_f32_e32 v3, v3, v139
	v_mul_f32_e32 v206, 0xbfb8aa3b, v12
	v_mul_f32_e32 v207, 0xbfb8aa3b, v13
	v_mul_f32_e32 v208, 0xbfb8aa3b, v14
	v_mul_f32_e32 v209, 0xbfb8aa3b, v15
	v_mul_f32_e32 v210, 0xbfb8aa3b, v4
	v_mul_f32_e32 v211, 0xbfb8aa3b, v5
	v_mul_f32_e32 v212, 0xbfb8aa3b, v6
	v_mul_f32_e32 v213, 0xbfb8aa3b, v7
	v_exp_f32_e32 v206, v206
	v_exp_f32_e32 v207, v207
	v_exp_f32_e32 v208, v208
	v_exp_f32_e32 v209, v209
	v_exp_f32_e32 v210, v210
	v_exp_f32_e32 v211, v211
	v_exp_f32_e32 v212, v212
	v_exp_f32_e32 v213, v213
	v_add_f32_e32 v206, 1.0, v206
	v_add_f32_e32 v207, 1.0, v207
	v_add_f32_e32 v208, 1.0, v208
	v_add_f32_e32 v209, 1.0, v209
	v_add_f32_e32 v210, 1.0, v210
	v_add_f32_e32 v211, 1.0, v211
	v_add_f32_e32 v212, 1.0, v212
	v_add_f32_e32 v213, 1.0, v213
	v_rcp_f32_e32 v206, v206
	v_rcp_f32_e32 v207, v207
	v_rcp_f32_e32 v208, v208
	v_rcp_f32_e32 v209, v209
	v_rcp_f32_e32 v210, v210
	v_rcp_f32_e32 v211, v211
	v_rcp_f32_e32 v212, v212
	v_rcp_f32_e32 v213, v213
	v_mul_f32_e32 v12, v12, v206
	v_mul_f32_e32 v13, v13, v207
	v_mul_f32_e32 v14, v14, v208
	v_mul_f32_e32 v15, v15, v209
	v_mul_f32_e32 v4, v4, v210
	v_mul_f32_e32 v5, v5, v211
	v_mul_f32_e32 v6, v6, v212
	v_mul_f32_e32 v7, v7, v213
	v_mul_f32_e32 v8, v8, v12
	v_mul_f32_e32 v9, v9, v13
	v_mul_f32_e32 v10, v10, v14
	v_mul_f32_e32 v11, v11, v15
	v_mul_f32_e32 v0, v0, v4
	v_mul_f32_e32 v1, v1, v5
	v_mul_f32_e32 v2, v2, v6
	v_mul_f32_e32 v3, v3, v7
	v_cvt_pk_bf16_f32 v218, v8, v9
	v_cvt_pk_bf16_f32 v219, v10, v11
	v_cvt_pk_bf16_f32 v220, v0, v1
	v_cvt_pk_bf16_f32 v221, v2, v3
	global_store_dwordx4 v[222:223], v[218:221], off nt
	s_cbranch_vccnz .LBB0_666
	s_andn2_b64 vcc, exec, s[6:7]
	s_cbranch_vccnz .LBB0_665
	s_barrier
	s_branch .LBB0_665
